# phase0 w_in conversion tiles: the 8 guarded row-block loads of a tile issued together
# baseline (speedup 1.0000x reference)
.LBB0_51:
	s_andn2_b64 vcc, exec, s[10:11]
	s_cbranch_vccnz .LBB0_20
	s_load_dwordx2 s[10:11], s[2:3], 0x50
	s_mul_i32 s9, s8, 0x1a28000
	s_mul_hi_i32 s6, s8, 0x1a28000
	s_mul_hi_i32 s13, s12, 0x4d4873ed
	v_mov_b32_e32 v197, v196
	s_waitcnt lgkmcnt(0)
	s_add_u32 s14, s10, s9
	s_addc_u32 s15, s11, s6
	s_lshr_b32 s6, s13, 31
	s_ashr_i32 s9, s13, 5
	s_add_i32 s9, s9, s6
	s_mul_i32 s6, s9, 0x6a
	s_sub_i32 s6, s12, s6
	s_lshl_b32 s6, s6, 6
	v_lshlrev_b32_e32 v0, 2, v197
	v_and_b32_e32 v199, 60, v0
	v_or_b32_e32 v0, s6, v199
	s_cmpk_gt_u32 s6, 0x87f
	v_add_u32_e32 v1, 0xffffffa8, v0
	s_cselect_b64 vcc, -1, 0
	v_cndmask_b32_e32 v1, -1, v1, vcc
	v_cmp_gt_i32_e32 vcc, s31, v0
	v_ashrrev_i32_e32 v198, 4, v197
	s_lshl_b32 s10, s9, 7
	v_cndmask_b32_e32 v192, v1, v0, vcc
	v_mov_b32_e32 v0, 0
	v_cmp_lt_i32_e32 vcc, -1, v192
	v_add_u32_e32 v200, s10, v198
	v_lshl_add_u64 v[194:195], v[192:193], 2, s[14:15]
	v_mov_b32_e32 v1, v0
	v_mov_b32_e32 v2, v0
	v_mov_b32_e32 v3, v0
	v_mov_b64_e32 v[4:5], 0
	v_mov_b64_e32 v[6:7], 0
	v_mov_b64_e32 v[8:9], 0
	v_mov_b64_e32 v[10:11], 0
	v_mov_b64_e32 v[12:13], 0
	v_mov_b64_e32 v[14:15], 0
	v_mov_b64_e32 v[16:17], 0
	v_mov_b64_e32 v[18:19], 0
	v_mov_b64_e32 v[20:21], 0
	v_mov_b64_e32 v[22:23], 0
	v_mov_b64_e32 v[24:25], 0
	v_mov_b64_e32 v[26:27], 0
	v_mov_b64_e32 v[28:29], 0
	v_mov_b64_e32 v[30:31], 0
	s_load_dwordx2 s[12:13], s[2:3], 0xe0
	s_and_saveexec_b64 s[14:15], vcc
	s_cbranch_execz .Lcv_in_skip
	v_mad_i64_i32 v[32:33], s[36:37], v200, s33, v[194:195]
	v_add_u32_e32 v48, 16, v200
	v_mad_i64_i32 v[34:35], s[36:37], v48, s33, v[194:195]
	v_add_u32_e32 v48, 32, v200
	v_mad_i64_i32 v[36:37], s[36:37], v48, s33, v[194:195]
	v_add_u32_e32 v48, 48, v200
	v_mad_i64_i32 v[38:39], s[36:37], v48, s33, v[194:195]
	v_add_u32_e32 v48, 64, v200
	v_mad_i64_i32 v[40:41], s[36:37], v48, s33, v[194:195]
	v_add_u32_e32 v48, 80, v200
	v_mad_i64_i32 v[42:43], s[36:37], v48, s33, v[194:195]
	v_add_u32_e32 v48, 96, v200
	v_mad_i64_i32 v[44:45], s[36:37], v48, s33, v[194:195]
	v_add_u32_e32 v48, 112, v200
	v_mad_i64_i32 v[46:47], s[36:37], v48, s33, v[194:195]
	global_load_dwordx4 v[0:3], v[32:33], off nt
	global_load_dwordx4 v[4:7], v[34:35], off nt
	global_load_dwordx4 v[8:11], v[36:37], off nt
	global_load_dwordx4 v[12:15], v[38:39], off nt
	global_load_dwordx4 v[16:19], v[40:41], off nt
	global_load_dwordx4 v[20:23], v[42:43], off nt
	global_load_dwordx4 v[24:27], v[44:45], off nt
	global_load_dwordx4 v[28:31], v[46:47], off nt
.Lcv_in_skip:
	s_waitcnt vmcnt(0)
	s_branch .LBB0_19
